# phase 4: every other group of eight workgroups starts its seven tiles one s_sleep 127 late (output bursts of the two halves alternate)
# speedup vs baseline: 1.0258x; 1.0009x over previous
.LBB0_577:
.LBB0_578:
	s_cmp_lt_i32 s68, 5
	s_cselect_b64 s[6:7], -1, 0
	v_readlane_b32 s72, v240, 0
	s_and_b64 s[14:15], s[6:7], s[4:5]
	v_readlane_b32 s73, v240, 1
	s_andn2_b64 vcc, exec, s[14:15]
	s_cbranch_vccnz .LBB0_629
	s_cmpk_lg_u32 s70, 0x100
	s_cbranch_scc1 .Lp4_go
	s_bitcmp1_b32 s2, 3
	s_cbranch_scc0 .Lp4_go
	s_sleep 127
.Lp4_go:
	s_add_u32 s76, s66, 0x1c00000
	s_addc_u32 s77, s67, 0
	s_cmpk_lt_i32 s2, 0x700
	s_cselect_b64 s[4:5], -1, 0
	s_cmpk_gt_i32 s2, 0x6ff
	v_readfirstlane_b32 s6, v1
	s_cbranch_scc1 .LBB0_581
	s_ashr_i32 s7, s2, 31
	s_lshr_b32 s7, s7, 29
	s_add_i32 s7, s2, s7
	s_ashr_i32 s8, s7, 3
	s_and_b32 s7, s7, -8
	s_sub_i32 s7, s2, s7
	s_cmp_lt_i32 s7, 0
	s_movk_i32 s9, 0xe1
	s_cselect_b32 s9, s9, 0xe0
	s_mul_i32 s7, s7, s9
	s_add_i32 s7, s7, s8
	s_mul_hi_i32 s8, s7, 0x92492493
	s_add_i32 s8, s8, s7
	s_lshr_b32 s9, s8, 31
	s_ashr_i32 s8, s8, 6
	s_add_i32 s8, s8, s9
	s_lshl_b32 s9, s8, 2
	s_mulk_i32 s8, 0x70
	s_sub_i32 s7, s7, s8
	s_bfe_i32 s8, s7, 0x80000
	s_bfe_u32 s8, s8, 0x2000d
	s_add_i32 s8, s7, s8
	s_bfe_i32 s10, s8, 0x80000
	s_and_b32 s8, s8, 0xfc
	s_sub_i32 s7, s7, s8
	s_sext_i32_i8 s7, s7
	s_add_i32 s60, s9, s7
	s_sext_i32_i16 s12, s10
	s_ashr_i32 s61, s60, 31
	s_ashr_i32 s97, s12, 2
	s_lshl_b64 s[8:9], s[60:61], 19
	s_add_u32 s10, s76, s8
	s_addc_u32 s11, s77, s9
	s_ashr_i32 s7, s12, 4
	s_lshl_b32 s8, s7, 10
	s_add_i32 s9, s8, 0xc00
	s_cmp_lt_i32 s7, 5
	s_cselect_b32 s7, s8, s9
	s_lshl_b32 s8, s97, 8
	s_and_b32 s8, s8, 0x300
	s_or_b32 s8, s7, s8
	s_ashr_i32 s9, s8, 31
	s_lshl_b64 s[8:9], s[8:9], 11
	s_add_u32 s12, s66, s8
	s_addc_u32 s13, s67, s9
	s_andn2_b64 vcc, exec, s[4:5]
	s_cbranch_vccz .LBB0_582
	s_branch .LBB0_629
